# P0: adaLN GEMV tasks dealt 6 per workgroup (was 8 per workgroup on the first 192) + dtype comment
# baseline (speedup 1.0000x reference)
; __device__ __forceinline__ void phase_prologue(Ctx& X) {
;     ...
;     for (int task = X.gw; task < 48 * 32; task += X.NGW) {
;         const int cb = task % 48, ks = task / 48;
;         const f32x4* wp = (const f32x4*)(X.w_ada + (size_t)(ks * 64) * NMOD + cb * 256) + X.lane;
;         f32x4 a = (f32x4){0.f, 0.f, 0.f, 0.f};
; #pragma unroll 8
;         for (int i = 0; i < 64; ++i) { const float cv = X.c[ks * 64 + i]; const float sv = cv / (1.f + __expf(-cv)); a += __builtin_nontemporal_load(wp + (size_t)i * (NMOD / 4)) * sv; }
;         if (ks == 0) a += *((const f32x4*)(X.b_ada + cb * 256) + X.lane);
;         float* mp = mod + cb * 256 + X.lane * 4;
;         atomicAdd(mp + 0, a[0]); atomicAdd(mp + 1, a[1]); atomicAdd(mp + 2, a[2]); atomicAdd(mp + 3, a[3]);
;     }
.LBB0_19:
	s_load_dwordx16 s[52:67], s[0:1], 0x0
	s_load_dwordx16 s[4:19], s[0:1], 0x40
	s_lshr_b32 s97, s20, 6
	s_lshl_b32 s50, s94, 3
	v_and_b32_e32 v208, 63, v209
	s_waitcnt lgkmcnt(0)
	v_writelane_b32 v245, s4, 5
	s_nop 1
	v_writelane_b32 v245, s5, 6
	v_writelane_b32 v245, s6, 7
	v_writelane_b32 v245, s7, 8
	v_writelane_b32 v245, s8, 9
	v_writelane_b32 v245, s9, 10
	v_writelane_b32 v245, s10, 11
	v_writelane_b32 v245, s11, 12
	v_writelane_b32 v245, s12, 13
	v_writelane_b32 v245, s13, 14
	v_writelane_b32 v245, s14, 15
	v_writelane_b32 v245, s15, 16
	v_writelane_b32 v245, s16, 17
	v_writelane_b32 v245, s17, 18
	v_writelane_b32 v245, s18, 19
	v_writelane_b32 v245, s19, 20
	v_writelane_b32 v245, s20, 21
	s_nop 0
	v_readlane_b32 s0, v245, 0
	s_lshl_b32 s0, s0, 3
	s_add_i32 s48, s97, s0
	v_readlane_b32 s1, v245, 1
	s_cmp_lt_i32 s92, 1
	v_writelane_b32 v245, s0, 22
	s_cselect_b64 s[0:1], -1, 0
	s_cmp_gt_i32 s93, 0
	s_cselect_b64 s[2:3], -1, 0
	s_and_b64 s[16:17], s[0:1], s[2:3]
	s_andn2_b64 vcc, exec, s[16:17]
	s_cbranch_vccnz .LBB0_50
	s_cmp_lg_u32 s94, 0x100
	s_cbranch_scc1 .Lp0_orig
	s_and_b32 s0, s48, 7
	s_lshl_b32 s0, s0, 8
	s_lshr_b32 s1, s48, 3
	s_add_i32 s31, s0, s1
	s_branch .Lp0_go
.Lp0_orig:
	s_mov_b32 s31, s48
.Lp0_go:
	s_cmpk_gt_i32 s31, 0x5ff
	s_cbranch_scc1 .LBB0_27
	v_mov_b32_e32 v9, 0
	v_lshlrev_b32_e32 v8, 4, v208
	s_add_u32 s2, s54, 28
	v_lshl_add_u64 v[10:11], s[60:61], 0, v[8:9]
	v_lshl_add_u64 v[12:13], s[90:91], 0, v[8:9]
	s_addc_u32 s3, s55, 0
	s_mov_b32 s24, 0xc000
	v_lshlrev_b32_e32 v8, 4, v208
	s_mov_b32 s25, 0x18000
	s_mov_b32 s26, 0x24000
	s_mov_b32 s27, 0x30000
	s_mov_b32 s28, 0x3c000
	s_mov_b32 s29, 0x48000
	s_mov_b32 s30, 0x54000
	s_branch .LBB0_23
